# P1 gate tiles hand-written: packed f32 ops, SDWA byte inserts, scalar-base store addressing
# baseline (speedup 1.0000x reference)
.LBB0_218:
	s_lshl_b32 s1, s4, 8
	v_lshl_add_u32 v160, s0, 8, v139
	v_or_b32_e32 v136, s1, v153
	s_cmp_gt_i32 s4, 3
	s_mov_b64 s[2:3], -1
	s_cbranch_scc0 .LBB0_256
	s_cmp_gt_u32 s4, 13
	s_cbranch_scc0 .LBB0_221
	v_readfirstlane_b32 s10, v214
	v_readlane_b32 s2, v246, 26
	v_readlane_b32 s3, v246, 27
	v_and_b32_e32 v148, 15, v214
	v_bfe_u32 v150, v214, 4, 2
	v_mul_u32_u24_e32 v148, 0x2c00, v148
	v_lshl_add_u32 v148, v150, 4, v148
	s_lshr_b32 s11, s10, 8
	s_lshl_b32 s11, s11, 6
	s_lshl_b32 s66, s0, 8
	s_add_u32 s11, s11, s66
	s_mul_i32 s11, s11, 0x2c00
	s_bfe_u32 s10, s10, 0x20006
	s_lshl_b32 s10, s10, 6
	s_sub_u32 s66, s4, 14
	s_lshl_b32 s66, s66, 8
	s_add_u32 s10, s10, s66
	s_add_u32 s10, s10, 0x1c00
	s_add_u32 s66, s2, s11
	s_addc_u32 s67, s3, 0
	s_add_u32 s66, s66, s10
	s_addc_u32 s67, s67, 0
	s_mov_b32 s68, 0xbfb8aa3b
	v_pk_mul_f32 v[112:113], v[112:113], s[68:69] op_sel_hi:[1,0]
	v_pk_mul_f32 v[114:115], v[114:115], s[68:69] op_sel_hi:[1,0]
	v_pk_mul_f32 v[116:117], v[116:117], s[68:69] op_sel_hi:[1,0]
	v_pk_mul_f32 v[118:119], v[118:119], s[68:69] op_sel_hi:[1,0]
	v_pk_mul_f32 v[120:121], v[120:121], s[68:69] op_sel_hi:[1,0]
	v_pk_mul_f32 v[122:123], v[122:123], s[68:69] op_sel_hi:[1,0]
	v_pk_mul_f32 v[124:125], v[124:125], s[68:69] op_sel_hi:[1,0]
	v_pk_mul_f32 v[126:127], v[126:127], s[68:69] op_sel_hi:[1,0]
	v_exp_f32_e32 v112, v112
	v_exp_f32_e32 v113, v113
	v_exp_f32_e32 v114, v114
	v_exp_f32_e32 v115, v115
	v_exp_f32_e32 v116, v116
	v_exp_f32_e32 v117, v117
	v_exp_f32_e32 v118, v118
	v_exp_f32_e32 v119, v119
	v_exp_f32_e32 v120, v120
	v_exp_f32_e32 v121, v121
	v_exp_f32_e32 v122, v122
	v_exp_f32_e32 v123, v123
	v_exp_f32_e32 v124, v124
	v_exp_f32_e32 v125, v125
	v_exp_f32_e32 v126, v126
	v_exp_f32_e32 v127, v127
	v_pk_add_f32 v[112:113], v[112:113], 1.0 op_sel_hi:[1,0]
	v_pk_add_f32 v[114:115], v[114:115], 1.0 op_sel_hi:[1,0]
	v_pk_add_f32 v[116:117], v[116:117], 1.0 op_sel_hi:[1,0]
	v_pk_add_f32 v[118:119], v[118:119], 1.0 op_sel_hi:[1,0]
	v_pk_add_f32 v[120:121], v[120:121], 1.0 op_sel_hi:[1,0]
	v_pk_add_f32 v[122:123], v[122:123], 1.0 op_sel_hi:[1,0]
	v_pk_add_f32 v[124:125], v[124:125], 1.0 op_sel_hi:[1,0]
	v_pk_add_f32 v[126:127], v[126:127], 1.0 op_sel_hi:[1,0]
	v_rcp_f32_e32 v112, v112
	v_rcp_f32_e32 v113, v113
	v_rcp_f32_e32 v114, v114
	v_rcp_f32_e32 v115, v115
	v_rcp_f32_e32 v116, v116
	v_rcp_f32_e32 v117, v117
	v_rcp_f32_e32 v118, v118
	v_rcp_f32_e32 v119, v119
	v_rcp_f32_e32 v120, v120
	v_rcp_f32_e32 v121, v121
	v_rcp_f32_e32 v122, v122
	v_rcp_f32_e32 v123, v123
	v_rcp_f32_e32 v124, v124
	v_rcp_f32_e32 v125, v125
	v_rcp_f32_e32 v126, v126
	v_rcp_f32_e32 v127, v127
	v_pk_fma_f32 v[112:113], v[112:113], s[24:25], 0.5 op_sel_hi:[1,0,0]
	v_pk_fma_f32 v[114:115], v[114:115], s[24:25], 0.5 op_sel_hi:[1,0,0]
	v_pk_fma_f32 v[116:117], v[116:117], s[24:25], 0.5 op_sel_hi:[1,0,0]
	v_pk_fma_f32 v[118:119], v[118:119], s[24:25], 0.5 op_sel_hi:[1,0,0]
	v_pk_fma_f32 v[120:121], v[120:121], s[24:25], 0.5 op_sel_hi:[1,0,0]
	v_pk_fma_f32 v[122:123], v[122:123], s[24:25], 0.5 op_sel_hi:[1,0,0]
	v_pk_fma_f32 v[124:125], v[124:125], s[24:25], 0.5 op_sel_hi:[1,0,0]
	v_pk_fma_f32 v[126:127], v[126:127], s[24:25], 0.5 op_sel_hi:[1,0,0]
	v_cvt_u32_f32_e32 v160, v124
	v_cvt_u32_f32_e32 v161, v116
	v_cvt_u32_f32_e32 v162, v120
	v_cvt_u32_f32_e32 v163, v112
	v_cvt_u32_f32_sdwa v160, v125 dst_sel:BYTE_1 dst_unused:UNUSED_PRESERVE src0_sel:DWORD
	v_cvt_u32_f32_sdwa v161, v117 dst_sel:BYTE_1 dst_unused:UNUSED_PRESERVE src0_sel:DWORD
	v_cvt_u32_f32_sdwa v162, v121 dst_sel:BYTE_1 dst_unused:UNUSED_PRESERVE src0_sel:DWORD
	v_cvt_u32_f32_sdwa v163, v113 dst_sel:BYTE_1 dst_unused:UNUSED_PRESERVE src0_sel:DWORD
	v_cvt_u32_f32_sdwa v160, v126 dst_sel:BYTE_2 dst_unused:UNUSED_PRESERVE src0_sel:DWORD
	v_cvt_u32_f32_sdwa v161, v118 dst_sel:BYTE_2 dst_unused:UNUSED_PRESERVE src0_sel:DWORD
	v_cvt_u32_f32_sdwa v162, v122 dst_sel:BYTE_2 dst_unused:UNUSED_PRESERVE src0_sel:DWORD
	v_cvt_u32_f32_sdwa v163, v114 dst_sel:BYTE_2 dst_unused:UNUSED_PRESERVE src0_sel:DWORD
	v_cvt_u32_f32_sdwa v160, v127 dst_sel:BYTE_3 dst_unused:UNUSED_PRESERVE src0_sel:DWORD
	v_cvt_u32_f32_sdwa v161, v119 dst_sel:BYTE_3 dst_unused:UNUSED_PRESERVE src0_sel:DWORD
	v_cvt_u32_f32_sdwa v162, v123 dst_sel:BYTE_3 dst_unused:UNUSED_PRESERVE src0_sel:DWORD
	v_cvt_u32_f32_sdwa v163, v115 dst_sel:BYTE_3 dst_unused:UNUSED_PRESERVE src0_sel:DWORD
	s_nop 0
	global_store_dwordx4 v148, v[160:163], s[66:67] nt
	s_add_u32 s66, s66, 0x2c000
	s_addc_u32 s67, s67, 0
	v_pk_mul_f32 v[96:97], v[96:97], s[68:69] op_sel_hi:[1,0]
	v_pk_mul_f32 v[98:99], v[98:99], s[68:69] op_sel_hi:[1,0]
	v_pk_mul_f32 v[100:101], v[100:101], s[68:69] op_sel_hi:[1,0]
	v_pk_mul_f32 v[102:103], v[102:103], s[68:69] op_sel_hi:[1,0]
	v_pk_mul_f32 v[104:105], v[104:105], s[68:69] op_sel_hi:[1,0]
	v_pk_mul_f32 v[106:107], v[106:107], s[68:69] op_sel_hi:[1,0]
	v_pk_mul_f32 v[108:109], v[108:109], s[68:69] op_sel_hi:[1,0]
	v_pk_mul_f32 v[110:111], v[110:111], s[68:69] op_sel_hi:[1,0]
	v_exp_f32_e32 v96, v96
	v_exp_f32_e32 v97, v97
	v_exp_f32_e32 v98, v98
	v_exp_f32_e32 v99, v99
	v_exp_f32_e32 v100, v100
	v_exp_f32_e32 v101, v101
	v_exp_f32_e32 v102, v102
	v_exp_f32_e32 v103, v103
	v_exp_f32_e32 v104, v104
	v_exp_f32_e32 v105, v105
	v_exp_f32_e32 v106, v106
	v_exp_f32_e32 v107, v107
	v_exp_f32_e32 v108, v108
	v_exp_f32_e32 v109, v109
	v_exp_f32_e32 v110, v110
	v_exp_f32_e32 v111, v111
	v_pk_add_f32 v[96:97], v[96:97], 1.0 op_sel_hi:[1,0]
	v_pk_add_f32 v[98:99], v[98:99], 1.0 op_sel_hi:[1,0]
	v_pk_add_f32 v[100:101], v[100:101], 1.0 op_sel_hi:[1,0]
	v_pk_add_f32 v[102:103], v[102:103], 1.0 op_sel_hi:[1,0]
	v_pk_add_f32 v[104:105], v[104:105], 1.0 op_sel_hi:[1,0]
	v_pk_add_f32 v[106:107], v[106:107], 1.0 op_sel_hi:[1,0]
	v_pk_add_f32 v[108:109], v[108:109], 1.0 op_sel_hi:[1,0]
	v_pk_add_f32 v[110:111], v[110:111], 1.0 op_sel_hi:[1,0]
	v_rcp_f32_e32 v96, v96
	v_rcp_f32_e32 v97, v97
	v_rcp_f32_e32 v98, v98
	v_rcp_f32_e32 v99, v99
	v_rcp_f32_e32 v100, v100
	v_rcp_f32_e32 v101, v101
	v_rcp_f32_e32 v102, v102
	v_rcp_f32_e32 v103, v103
	v_rcp_f32_e32 v104, v104
	v_rcp_f32_e32 v105, v105
	v_rcp_f32_e32 v106, v106
	v_rcp_f32_e32 v107, v107
	v_rcp_f32_e32 v108, v108
	v_rcp_f32_e32 v109, v109
	v_rcp_f32_e32 v110, v110
	v_rcp_f32_e32 v111, v111
	v_pk_fma_f32 v[96:97], v[96:97], s[24:25], 0.5 op_sel_hi:[1,0,0]
	v_pk_fma_f32 v[98:99], v[98:99], s[24:25], 0.5 op_sel_hi:[1,0,0]
	v_pk_fma_f32 v[100:101], v[100:101], s[24:25], 0.5 op_sel_hi:[1,0,0]
	v_pk_fma_f32 v[102:103], v[102:103], s[24:25], 0.5 op_sel_hi:[1,0,0]
	v_pk_fma_f32 v[104:105], v[104:105], s[24:25], 0.5 op_sel_hi:[1,0,0]
	v_pk_fma_f32 v[106:107], v[106:107], s[24:25], 0.5 op_sel_hi:[1,0,0]
	v_pk_fma_f32 v[108:109], v[108:109], s[24:25], 0.5 op_sel_hi:[1,0,0]
	v_pk_fma_f32 v[110:111], v[110:111], s[24:25], 0.5 op_sel_hi:[1,0,0]
	v_cvt_u32_f32_e32 v164, v108
	v_cvt_u32_f32_e32 v165, v100
	v_cvt_u32_f32_e32 v166, v104
	v_cvt_u32_f32_e32 v167, v96
	v_cvt_u32_f32_sdwa v164, v109 dst_sel:BYTE_1 dst_unused:UNUSED_PRESERVE src0_sel:DWORD
	v_cvt_u32_f32_sdwa v165, v101 dst_sel:BYTE_1 dst_unused:UNUSED_PRESERVE src0_sel:DWORD
	v_cvt_u32_f32_sdwa v166, v105 dst_sel:BYTE_1 dst_unused:UNUSED_PRESERVE src0_sel:DWORD
	v_cvt_u32_f32_sdwa v167, v97 dst_sel:BYTE_1 dst_unused:UNUSED_PRESERVE src0_sel:DWORD
	v_cvt_u32_f32_sdwa v164, v110 dst_sel:BYTE_2 dst_unused:UNUSED_PRESERVE src0_sel:DWORD
	v_cvt_u32_f32_sdwa v165, v102 dst_sel:BYTE_2 dst_unused:UNUSED_PRESERVE src0_sel:DWORD
	v_cvt_u32_f32_sdwa v166, v106 dst_sel:BYTE_2 dst_unused:UNUSED_PRESERVE src0_sel:DWORD
	v_cvt_u32_f32_sdwa v167, v98 dst_sel:BYTE_2 dst_unused:UNUSED_PRESERVE src0_sel:DWORD
	v_cvt_u32_f32_sdwa v164, v111 dst_sel:BYTE_3 dst_unused:UNUSED_PRESERVE src0_sel:DWORD
	v_cvt_u32_f32_sdwa v165, v103 dst_sel:BYTE_3 dst_unused:UNUSED_PRESERVE src0_sel:DWORD
	v_cvt_u32_f32_sdwa v166, v107 dst_sel:BYTE_3 dst_unused:UNUSED_PRESERVE src0_sel:DWORD
	v_cvt_u32_f32_sdwa v167, v99 dst_sel:BYTE_3 dst_unused:UNUSED_PRESERVE src0_sel:DWORD
	s_nop 0
	global_store_dwordx4 v148, v[164:167], s[66:67] nt
	s_add_u32 s66, s66, 0x2c000
	s_addc_u32 s67, s67, 0
	v_pk_mul_f32 v[80:81], v[80:81], s[68:69] op_sel_hi:[1,0]
	v_pk_mul_f32 v[82:83], v[82:83], s[68:69] op_sel_hi:[1,0]
	v_pk_mul_f32 v[84:85], v[84:85], s[68:69] op_sel_hi:[1,0]
	v_pk_mul_f32 v[86:87], v[86:87], s[68:69] op_sel_hi:[1,0]
	v_pk_mul_f32 v[88:89], v[88:89], s[68:69] op_sel_hi:[1,0]
	v_pk_mul_f32 v[90:91], v[90:91], s[68:69] op_sel_hi:[1,0]
	v_pk_mul_f32 v[92:93], v[92:93], s[68:69] op_sel_hi:[1,0]
	v_pk_mul_f32 v[94:95], v[94:95], s[68:69] op_sel_hi:[1,0]
	v_exp_f32_e32 v80, v80
	v_exp_f32_e32 v81, v81
	v_exp_f32_e32 v82, v82
	v_exp_f32_e32 v83, v83
	v_exp_f32_e32 v84, v84
	v_exp_f32_e32 v85, v85
	v_exp_f32_e32 v86, v86
	v_exp_f32_e32 v87, v87
	v_exp_f32_e32 v88, v88
	v_exp_f32_e32 v89, v89
	v_exp_f32_e32 v90, v90
	v_exp_f32_e32 v91, v91
	v_exp_f32_e32 v92, v92
	v_exp_f32_e32 v93, v93
	v_exp_f32_e32 v94, v94
	v_exp_f32_e32 v95, v95
	v_pk_add_f32 v[80:81], v[80:81], 1.0 op_sel_hi:[1,0]
	v_pk_add_f32 v[82:83], v[82:83], 1.0 op_sel_hi:[1,0]
	v_pk_add_f32 v[84:85], v[84:85], 1.0 op_sel_hi:[1,0]
	v_pk_add_f32 v[86:87], v[86:87], 1.0 op_sel_hi:[1,0]
	v_pk_add_f32 v[88:89], v[88:89], 1.0 op_sel_hi:[1,0]
	v_pk_add_f32 v[90:91], v[90:91], 1.0 op_sel_hi:[1,0]
	v_pk_add_f32 v[92:93], v[92:93], 1.0 op_sel_hi:[1,0]
	v_pk_add_f32 v[94:95], v[94:95], 1.0 op_sel_hi:[1,0]
	v_rcp_f32_e32 v80, v80
	v_rcp_f32_e32 v81, v81
	v_rcp_f32_e32 v82, v82
	v_rcp_f32_e32 v83, v83
	v_rcp_f32_e32 v84, v84
	v_rcp_f32_e32 v85, v85
	v_rcp_f32_e32 v86, v86
	v_rcp_f32_e32 v87, v87
	v_rcp_f32_e32 v88, v88
	v_rcp_f32_e32 v89, v89
	v_rcp_f32_e32 v90, v90
	v_rcp_f32_e32 v91, v91
	v_rcp_f32_e32 v92, v92
	v_rcp_f32_e32 v93, v93
	v_rcp_f32_e32 v94, v94
	v_rcp_f32_e32 v95, v95
	v_pk_fma_f32 v[80:81], v[80:81], s[24:25], 0.5 op_sel_hi:[1,0,0]
	v_pk_fma_f32 v[82:83], v[82:83], s[24:25], 0.5 op_sel_hi:[1,0,0]
	v_pk_fma_f32 v[84:85], v[84:85], s[24:25], 0.5 op_sel_hi:[1,0,0]
	v_pk_fma_f32 v[86:87], v[86:87], s[24:25], 0.5 op_sel_hi:[1,0,0]
	v_pk_fma_f32 v[88:89], v[88:89], s[24:25], 0.5 op_sel_hi:[1,0,0]
	v_pk_fma_f32 v[90:91], v[90:91], s[24:25], 0.5 op_sel_hi:[1,0,0]
	v_pk_fma_f32 v[92:93], v[92:93], s[24:25], 0.5 op_sel_hi:[1,0,0]
	v_pk_fma_f32 v[94:95], v[94:95], s[24:25], 0.5 op_sel_hi:[1,0,0]
	v_cvt_u32_f32_e32 v160, v92
	v_cvt_u32_f32_e32 v161, v84
	v_cvt_u32_f32_e32 v162, v88
	v_cvt_u32_f32_e32 v163, v80
	v_cvt_u32_f32_sdwa v160, v93 dst_sel:BYTE_1 dst_unused:UNUSED_PRESERVE src0_sel:DWORD
	v_cvt_u32_f32_sdwa v161, v85 dst_sel:BYTE_1 dst_unused:UNUSED_PRESERVE src0_sel:DWORD
	v_cvt_u32_f32_sdwa v162, v89 dst_sel:BYTE_1 dst_unused:UNUSED_PRESERVE src0_sel:DWORD
	v_cvt_u32_f32_sdwa v163, v81 dst_sel:BYTE_1 dst_unused:UNUSED_PRESERVE src0_sel:DWORD
	v_cvt_u32_f32_sdwa v160, v94 dst_sel:BYTE_2 dst_unused:UNUSED_PRESERVE src0_sel:DWORD
	v_cvt_u32_f32_sdwa v161, v86 dst_sel:BYTE_2 dst_unused:UNUSED_PRESERVE src0_sel:DWORD
	v_cvt_u32_f32_sdwa v162, v90 dst_sel:BYTE_2 dst_unused:UNUSED_PRESERVE src0_sel:DWORD
	v_cvt_u32_f32_sdwa v163, v82 dst_sel:BYTE_2 dst_unused:UNUSED_PRESERVE src0_sel:DWORD
	v_cvt_u32_f32_sdwa v160, v95 dst_sel:BYTE_3 dst_unused:UNUSED_PRESERVE src0_sel:DWORD
	v_cvt_u32_f32_sdwa v161, v87 dst_sel:BYTE_3 dst_unused:UNUSED_PRESERVE src0_sel:DWORD
	v_cvt_u32_f32_sdwa v162, v91 dst_sel:BYTE_3 dst_unused:UNUSED_PRESERVE src0_sel:DWORD
	v_cvt_u32_f32_sdwa v163, v83 dst_sel:BYTE_3 dst_unused:UNUSED_PRESERVE src0_sel:DWORD
	s_nop 0
	global_store_dwordx4 v148, v[160:163], s[66:67] nt
	s_add_u32 s66, s66, 0x2c000
	s_addc_u32 s67, s67, 0
	v_pk_mul_f32 v[64:65], v[64:65], s[68:69] op_sel_hi:[1,0]
	v_pk_mul_f32 v[66:67], v[66:67], s[68:69] op_sel_hi:[1,0]
	v_pk_mul_f32 v[68:69], v[68:69], s[68:69] op_sel_hi:[1,0]
	v_pk_mul_f32 v[70:71], v[70:71], s[68:69] op_sel_hi:[1,0]
	v_pk_mul_f32 v[72:73], v[72:73], s[68:69] op_sel_hi:[1,0]
	v_pk_mul_f32 v[74:75], v[74:75], s[68:69] op_sel_hi:[1,0]
	v_pk_mul_f32 v[76:77], v[76:77], s[68:69] op_sel_hi:[1,0]
	v_pk_mul_f32 v[78:79], v[78:79], s[68:69] op_sel_hi:[1,0]
	v_exp_f32_e32 v64, v64
	v_exp_f32_e32 v65, v65
	v_exp_f32_e32 v66, v66
	v_exp_f32_e32 v67, v67
	v_exp_f32_e32 v68, v68
	v_exp_f32_e32 v69, v69
	v_exp_f32_e32 v70, v70
	v_exp_f32_e32 v71, v71
	v_exp_f32_e32 v72, v72
	v_exp_f32_e32 v73, v73
	v_exp_f32_e32 v74, v74
	v_exp_f32_e32 v75, v75
	v_exp_f32_e32 v76, v76
	v_exp_f32_e32 v77, v77
	v_exp_f32_e32 v78, v78
	v_exp_f32_e32 v79, v79
	v_pk_add_f32 v[64:65], v[64:65], 1.0 op_sel_hi:[1,0]
	v_pk_add_f32 v[66:67], v[66:67], 1.0 op_sel_hi:[1,0]
	v_pk_add_f32 v[68:69], v[68:69], 1.0 op_sel_hi:[1,0]
	v_pk_add_f32 v[70:71], v[70:71], 1.0 op_sel_hi:[1,0]
	v_pk_add_f32 v[72:73], v[72:73], 1.0 op_sel_hi:[1,0]
	v_pk_add_f32 v[74:75], v[74:75], 1.0 op_sel_hi:[1,0]
	v_pk_add_f32 v[76:77], v[76:77], 1.0 op_sel_hi:[1,0]
	v_pk_add_f32 v[78:79], v[78:79], 1.0 op_sel_hi:[1,0]
	v_rcp_f32_e32 v64, v64
	v_rcp_f32_e32 v65, v65
	v_rcp_f32_e32 v66, v66
	v_rcp_f32_e32 v67, v67
	v_rcp_f32_e32 v68, v68
	v_rcp_f32_e32 v69, v69
	v_rcp_f32_e32 v70, v70
	v_rcp_f32_e32 v71, v71
	v_rcp_f32_e32 v72, v72
	v_rcp_f32_e32 v73, v73
	v_rcp_f32_e32 v74, v74
	v_rcp_f32_e32 v75, v75
	v_rcp_f32_e32 v76, v76
	v_rcp_f32_e32 v77, v77
	v_rcp_f32_e32 v78, v78
	v_rcp_f32_e32 v79, v79
	v_pk_fma_f32 v[64:65], v[64:65], s[24:25], 0.5 op_sel_hi:[1,0,0]
	v_pk_fma_f32 v[66:67], v[66:67], s[24:25], 0.5 op_sel_hi:[1,0,0]
	v_pk_fma_f32 v[68:69], v[68:69], s[24:25], 0.5 op_sel_hi:[1,0,0]
	v_pk_fma_f32 v[70:71], v[70:71], s[24:25], 0.5 op_sel_hi:[1,0,0]
	v_pk_fma_f32 v[72:73], v[72:73], s[24:25], 0.5 op_sel_hi:[1,0,0]
	v_pk_fma_f32 v[74:75], v[74:75], s[24:25], 0.5 op_sel_hi:[1,0,0]
	v_pk_fma_f32 v[76:77], v[76:77], s[24:25], 0.5 op_sel_hi:[1,0,0]
	v_pk_fma_f32 v[78:79], v[78:79], s[24:25], 0.5 op_sel_hi:[1,0,0]
	v_cvt_u32_f32_e32 v164, v76
	v_cvt_u32_f32_e32 v165, v68
	v_cvt_u32_f32_e32 v166, v72
	v_cvt_u32_f32_e32 v167, v64
	v_cvt_u32_f32_sdwa v164, v77 dst_sel:BYTE_1 dst_unused:UNUSED_PRESERVE src0_sel:DWORD
	v_cvt_u32_f32_sdwa v165, v69 dst_sel:BYTE_1 dst_unused:UNUSED_PRESERVE src0_sel:DWORD
	v_cvt_u32_f32_sdwa v166, v73 dst_sel:BYTE_1 dst_unused:UNUSED_PRESERVE src0_sel:DWORD
	v_cvt_u32_f32_sdwa v167, v65 dst_sel:BYTE_1 dst_unused:UNUSED_PRESERVE src0_sel:DWORD
	v_cvt_u32_f32_sdwa v164, v78 dst_sel:BYTE_2 dst_unused:UNUSED_PRESERVE src0_sel:DWORD
	v_cvt_u32_f32_sdwa v165, v70 dst_sel:BYTE_2 dst_unused:UNUSED_PRESERVE src0_sel:DWORD
	v_cvt_u32_f32_sdwa v166, v74 dst_sel:BYTE_2 dst_unused:UNUSED_PRESERVE src0_sel:DWORD
	v_cvt_u32_f32_sdwa v167, v66 dst_sel:BYTE_2 dst_unused:UNUSED_PRESERVE src0_sel:DWORD
	v_cvt_u32_f32_sdwa v164, v79 dst_sel:BYTE_3 dst_unused:UNUSED_PRESERVE src0_sel:DWORD
	v_cvt_u32_f32_sdwa v165, v71 dst_sel:BYTE_3 dst_unused:UNUSED_PRESERVE src0_sel:DWORD
	v_cvt_u32_f32_sdwa v166, v75 dst_sel:BYTE_3 dst_unused:UNUSED_PRESERVE src0_sel:DWORD
	v_cvt_u32_f32_sdwa v167, v67 dst_sel:BYTE_3 dst_unused:UNUSED_PRESERVE src0_sel:DWORD
	s_nop 0
	global_store_dwordx4 v148, v[164:167], s[66:67] nt
	s_add_u32 s66, s66, 0xdc000
	s_addc_u32 s67, s67, 0
	v_pk_mul_f32 v[48:49], v[48:49], s[68:69] op_sel_hi:[1,0]
	v_pk_mul_f32 v[50:51], v[50:51], s[68:69] op_sel_hi:[1,0]
	v_pk_mul_f32 v[52:53], v[52:53], s[68:69] op_sel_hi:[1,0]
	v_pk_mul_f32 v[54:55], v[54:55], s[68:69] op_sel_hi:[1,0]
	v_pk_mul_f32 v[56:57], v[56:57], s[68:69] op_sel_hi:[1,0]
	v_pk_mul_f32 v[58:59], v[58:59], s[68:69] op_sel_hi:[1,0]
	v_pk_mul_f32 v[60:61], v[60:61], s[68:69] op_sel_hi:[1,0]
	v_pk_mul_f32 v[62:63], v[62:63], s[68:69] op_sel_hi:[1,0]
	v_exp_f32_e32 v48, v48
	v_exp_f32_e32 v49, v49
	v_exp_f32_e32 v50, v50
	v_exp_f32_e32 v51, v51
	v_exp_f32_e32 v52, v52
	v_exp_f32_e32 v53, v53
	v_exp_f32_e32 v54, v54
	v_exp_f32_e32 v55, v55
	v_exp_f32_e32 v56, v56
	v_exp_f32_e32 v57, v57
	v_exp_f32_e32 v58, v58
	v_exp_f32_e32 v59, v59
	v_exp_f32_e32 v60, v60
	v_exp_f32_e32 v61, v61
	v_exp_f32_e32 v62, v62
	v_exp_f32_e32 v63, v63
	v_pk_add_f32 v[48:49], v[48:49], 1.0 op_sel_hi:[1,0]
	v_pk_add_f32 v[50:51], v[50:51], 1.0 op_sel_hi:[1,0]
	v_pk_add_f32 v[52:53], v[52:53], 1.0 op_sel_hi:[1,0]
	v_pk_add_f32 v[54:55], v[54:55], 1.0 op_sel_hi:[1,0]
	v_pk_add_f32 v[56:57], v[56:57], 1.0 op_sel_hi:[1,0]
	v_pk_add_f32 v[58:59], v[58:59], 1.0 op_sel_hi:[1,0]
	v_pk_add_f32 v[60:61], v[60:61], 1.0 op_sel_hi:[1,0]
	v_pk_add_f32 v[62:63], v[62:63], 1.0 op_sel_hi:[1,0]
	v_rcp_f32_e32 v48, v48
	v_rcp_f32_e32 v49, v49
	v_rcp_f32_e32 v50, v50
	v_rcp_f32_e32 v51, v51
	v_rcp_f32_e32 v52, v52
	v_rcp_f32_e32 v53, v53
	v_rcp_f32_e32 v54, v54
	v_rcp_f32_e32 v55, v55
	v_rcp_f32_e32 v56, v56
	v_rcp_f32_e32 v57, v57
	v_rcp_f32_e32 v58, v58
	v_rcp_f32_e32 v59, v59
	v_rcp_f32_e32 v60, v60
	v_rcp_f32_e32 v61, v61
	v_rcp_f32_e32 v62, v62
	v_rcp_f32_e32 v63, v63
	v_pk_fma_f32 v[48:49], v[48:49], s[24:25], 0.5 op_sel_hi:[1,0,0]
	v_pk_fma_f32 v[50:51], v[50:51], s[24:25], 0.5 op_sel_hi:[1,0,0]
	v_pk_fma_f32 v[52:53], v[52:53], s[24:25], 0.5 op_sel_hi:[1,0,0]
	v_pk_fma_f32 v[54:55], v[54:55], s[24:25], 0.5 op_sel_hi:[1,0,0]
	v_pk_fma_f32 v[56:57], v[56:57], s[24:25], 0.5 op_sel_hi:[1,0,0]
	v_pk_fma_f32 v[58:59], v[58:59], s[24:25], 0.5 op_sel_hi:[1,0,0]
	v_pk_fma_f32 v[60:61], v[60:61], s[24:25], 0.5 op_sel_hi:[1,0,0]
	v_pk_fma_f32 v[62:63], v[62:63], s[24:25], 0.5 op_sel_hi:[1,0,0]
	v_cvt_u32_f32_e32 v160, v60
	v_cvt_u32_f32_e32 v161, v52
	v_cvt_u32_f32_e32 v162, v56
	v_cvt_u32_f32_e32 v163, v48
	v_cvt_u32_f32_sdwa v160, v61 dst_sel:BYTE_1 dst_unused:UNUSED_PRESERVE src0_sel:DWORD
	v_cvt_u32_f32_sdwa v161, v53 dst_sel:BYTE_1 dst_unused:UNUSED_PRESERVE src0_sel:DWORD
	v_cvt_u32_f32_sdwa v162, v57 dst_sel:BYTE_1 dst_unused:UNUSED_PRESERVE src0_sel:DWORD
	v_cvt_u32_f32_sdwa v163, v49 dst_sel:BYTE_1 dst_unused:UNUSED_PRESERVE src0_sel:DWORD
	v_cvt_u32_f32_sdwa v160, v62 dst_sel:BYTE_2 dst_unused:UNUSED_PRESERVE src0_sel:DWORD
	v_cvt_u32_f32_sdwa v161, v54 dst_sel:BYTE_2 dst_unused:UNUSED_PRESERVE src0_sel:DWORD
	v_cvt_u32_f32_sdwa v162, v58 dst_sel:BYTE_2 dst_unused:UNUSED_PRESERVE src0_sel:DWORD
	v_cvt_u32_f32_sdwa v163, v50 dst_sel:BYTE_2 dst_unused:UNUSED_PRESERVE src0_sel:DWORD
	v_cvt_u32_f32_sdwa v160, v63 dst_sel:BYTE_3 dst_unused:UNUSED_PRESERVE src0_sel:DWORD
	v_cvt_u32_f32_sdwa v161, v55 dst_sel:BYTE_3 dst_unused:UNUSED_PRESERVE src0_sel:DWORD
	v_cvt_u32_f32_sdwa v162, v59 dst_sel:BYTE_3 dst_unused:UNUSED_PRESERVE src0_sel:DWORD
	v_cvt_u32_f32_sdwa v163, v51 dst_sel:BYTE_3 dst_unused:UNUSED_PRESERVE src0_sel:DWORD
	s_nop 0
	global_store_dwordx4 v148, v[160:163], s[66:67] nt
	s_add_u32 s66, s66, 0x2c000
	s_addc_u32 s67, s67, 0
	v_pk_mul_f32 v[32:33], v[32:33], s[68:69] op_sel_hi:[1,0]
	v_pk_mul_f32 v[34:35], v[34:35], s[68:69] op_sel_hi:[1,0]
	v_pk_mul_f32 v[36:37], v[36:37], s[68:69] op_sel_hi:[1,0]
	v_pk_mul_f32 v[38:39], v[38:39], s[68:69] op_sel_hi:[1,0]
	v_pk_mul_f32 v[40:41], v[40:41], s[68:69] op_sel_hi:[1,0]
	v_pk_mul_f32 v[42:43], v[42:43], s[68:69] op_sel_hi:[1,0]
	v_pk_mul_f32 v[44:45], v[44:45], s[68:69] op_sel_hi:[1,0]
	v_pk_mul_f32 v[46:47], v[46:47], s[68:69] op_sel_hi:[1,0]
	v_exp_f32_e32 v32, v32
	v_exp_f32_e32 v33, v33
	v_exp_f32_e32 v34, v34
	v_exp_f32_e32 v35, v35
	v_exp_f32_e32 v36, v36
	v_exp_f32_e32 v37, v37
	v_exp_f32_e32 v38, v38
	v_exp_f32_e32 v39, v39
	v_exp_f32_e32 v40, v40
	v_exp_f32_e32 v41, v41
	v_exp_f32_e32 v42, v42
	v_exp_f32_e32 v43, v43
	v_exp_f32_e32 v44, v44
	v_exp_f32_e32 v45, v45
	v_exp_f32_e32 v46, v46
	v_exp_f32_e32 v47, v47
	v_pk_add_f32 v[32:33], v[32:33], 1.0 op_sel_hi:[1,0]
	v_pk_add_f32 v[34:35], v[34:35], 1.0 op_sel_hi:[1,0]
	v_pk_add_f32 v[36:37], v[36:37], 1.0 op_sel_hi:[1,0]
	v_pk_add_f32 v[38:39], v[38:39], 1.0 op_sel_hi:[1,0]
	v_pk_add_f32 v[40:41], v[40:41], 1.0 op_sel_hi:[1,0]
	v_pk_add_f32 v[42:43], v[42:43], 1.0 op_sel_hi:[1,0]
	v_pk_add_f32 v[44:45], v[44:45], 1.0 op_sel_hi:[1,0]
	v_pk_add_f32 v[46:47], v[46:47], 1.0 op_sel_hi:[1,0]
	v_rcp_f32_e32 v32, v32
	v_rcp_f32_e32 v33, v33
	v_rcp_f32_e32 v34, v34
	v_rcp_f32_e32 v35, v35
	v_rcp_f32_e32 v36, v36
	v_rcp_f32_e32 v37, v37
	v_rcp_f32_e32 v38, v38
	v_rcp_f32_e32 v39, v39
	v_rcp_f32_e32 v40, v40
	v_rcp_f32_e32 v41, v41
	v_rcp_f32_e32 v42, v42
	v_rcp_f32_e32 v43, v43
	v_rcp_f32_e32 v44, v44
	v_rcp_f32_e32 v45, v45
	v_rcp_f32_e32 v46, v46
	v_rcp_f32_e32 v47, v47
	v_pk_fma_f32 v[32:33], v[32:33], s[24:25], 0.5 op_sel_hi:[1,0,0]
	v_pk_fma_f32 v[34:35], v[34:35], s[24:25], 0.5 op_sel_hi:[1,0,0]
	v_pk_fma_f32 v[36:37], v[36:37], s[24:25], 0.5 op_sel_hi:[1,0,0]
	v_pk_fma_f32 v[38:39], v[38:39], s[24:25], 0.5 op_sel_hi:[1,0,0]
	v_pk_fma_f32 v[40:41], v[40:41], s[24:25], 0.5 op_sel_hi:[1,0,0]
	v_pk_fma_f32 v[42:43], v[42:43], s[24:25], 0.5 op_sel_hi:[1,0,0]
	v_pk_fma_f32 v[44:45], v[44:45], s[24:25], 0.5 op_sel_hi:[1,0,0]
	v_pk_fma_f32 v[46:47], v[46:47], s[24:25], 0.5 op_sel_hi:[1,0,0]
	v_cvt_u32_f32_e32 v164, v44
	v_cvt_u32_f32_e32 v165, v36
	v_cvt_u32_f32_e32 v166, v40
	v_cvt_u32_f32_e32 v167, v32
	v_cvt_u32_f32_sdwa v164, v45 dst_sel:BYTE_1 dst_unused:UNUSED_PRESERVE src0_sel:DWORD
	v_cvt_u32_f32_sdwa v165, v37 dst_sel:BYTE_1 dst_unused:UNUSED_PRESERVE src0_sel:DWORD
	v_cvt_u32_f32_sdwa v166, v41 dst_sel:BYTE_1 dst_unused:UNUSED_PRESERVE src0_sel:DWORD
	v_cvt_u32_f32_sdwa v167, v33 dst_sel:BYTE_1 dst_unused:UNUSED_PRESERVE src0_sel:DWORD
	v_cvt_u32_f32_sdwa v164, v46 dst_sel:BYTE_2 dst_unused:UNUSED_PRESERVE src0_sel:DWORD
	v_cvt_u32_f32_sdwa v165, v38 dst_sel:BYTE_2 dst_unused:UNUSED_PRESERVE src0_sel:DWORD
	v_cvt_u32_f32_sdwa v166, v42 dst_sel:BYTE_2 dst_unused:UNUSED_PRESERVE src0_sel:DWORD
	v_cvt_u32_f32_sdwa v167, v34 dst_sel:BYTE_2 dst_unused:UNUSED_PRESERVE src0_sel:DWORD
	v_cvt_u32_f32_sdwa v164, v47 dst_sel:BYTE_3 dst_unused:UNUSED_PRESERVE src0_sel:DWORD
	v_cvt_u32_f32_sdwa v165, v39 dst_sel:BYTE_3 dst_unused:UNUSED_PRESERVE src0_sel:DWORD
	v_cvt_u32_f32_sdwa v166, v43 dst_sel:BYTE_3 dst_unused:UNUSED_PRESERVE src0_sel:DWORD
	v_cvt_u32_f32_sdwa v167, v35 dst_sel:BYTE_3 dst_unused:UNUSED_PRESERVE src0_sel:DWORD
	s_nop 0
	global_store_dwordx4 v148, v[164:167], s[66:67] nt
	s_add_u32 s66, s66, 0x2c000
	s_addc_u32 s67, s67, 0
	v_pk_mul_f32 v[16:17], v[16:17], s[68:69] op_sel_hi:[1,0]
	v_pk_mul_f32 v[18:19], v[18:19], s[68:69] op_sel_hi:[1,0]
	v_pk_mul_f32 v[20:21], v[20:21], s[68:69] op_sel_hi:[1,0]
	v_pk_mul_f32 v[22:23], v[22:23], s[68:69] op_sel_hi:[1,0]
	v_pk_mul_f32 v[24:25], v[24:25], s[68:69] op_sel_hi:[1,0]
	v_pk_mul_f32 v[26:27], v[26:27], s[68:69] op_sel_hi:[1,0]
	v_pk_mul_f32 v[28:29], v[28:29], s[68:69] op_sel_hi:[1,0]
	v_pk_mul_f32 v[30:31], v[30:31], s[68:69] op_sel_hi:[1,0]
	v_exp_f32_e32 v16, v16
	v_exp_f32_e32 v17, v17
	v_exp_f32_e32 v18, v18
	v_exp_f32_e32 v19, v19
	v_exp_f32_e32 v20, v20
	v_exp_f32_e32 v21, v21
	v_exp_f32_e32 v22, v22
	v_exp_f32_e32 v23, v23
	v_exp_f32_e32 v24, v24
	v_exp_f32_e32 v25, v25
	v_exp_f32_e32 v26, v26
	v_exp_f32_e32 v27, v27
	v_exp_f32_e32 v28, v28
	v_exp_f32_e32 v29, v29
	v_exp_f32_e32 v30, v30
	v_exp_f32_e32 v31, v31
	v_pk_add_f32 v[16:17], v[16:17], 1.0 op_sel_hi:[1,0]
	v_pk_add_f32 v[18:19], v[18:19], 1.0 op_sel_hi:[1,0]
	v_pk_add_f32 v[20:21], v[20:21], 1.0 op_sel_hi:[1,0]
	v_pk_add_f32 v[22:23], v[22:23], 1.0 op_sel_hi:[1,0]
	v_pk_add_f32 v[24:25], v[24:25], 1.0 op_sel_hi:[1,0]
	v_pk_add_f32 v[26:27], v[26:27], 1.0 op_sel_hi:[1,0]
	v_pk_add_f32 v[28:29], v[28:29], 1.0 op_sel_hi:[1,0]
	v_pk_add_f32 v[30:31], v[30:31], 1.0 op_sel_hi:[1,0]
	v_rcp_f32_e32 v16, v16
	v_rcp_f32_e32 v17, v17
	v_rcp_f32_e32 v18, v18
	v_rcp_f32_e32 v19, v19
	v_rcp_f32_e32 v20, v20
	v_rcp_f32_e32 v21, v21
	v_rcp_f32_e32 v22, v22
	v_rcp_f32_e32 v23, v23
	v_rcp_f32_e32 v24, v24
	v_rcp_f32_e32 v25, v25
	v_rcp_f32_e32 v26, v26
	v_rcp_f32_e32 v27, v27
	v_rcp_f32_e32 v28, v28
	v_rcp_f32_e32 v29, v29
	v_rcp_f32_e32 v30, v30
	v_rcp_f32_e32 v31, v31
	v_pk_fma_f32 v[16:17], v[16:17], s[24:25], 0.5 op_sel_hi:[1,0,0]
	v_pk_fma_f32 v[18:19], v[18:19], s[24:25], 0.5 op_sel_hi:[1,0,0]
	v_pk_fma_f32 v[20:21], v[20:21], s[24:25], 0.5 op_sel_hi:[1,0,0]
	v_pk_fma_f32 v[22:23], v[22:23], s[24:25], 0.5 op_sel_hi:[1,0,0]
	v_pk_fma_f32 v[24:25], v[24:25], s[24:25], 0.5 op_sel_hi:[1,0,0]
	v_pk_fma_f32 v[26:27], v[26:27], s[24:25], 0.5 op_sel_hi:[1,0,0]
	v_pk_fma_f32 v[28:29], v[28:29], s[24:25], 0.5 op_sel_hi:[1,0,0]
	v_pk_fma_f32 v[30:31], v[30:31], s[24:25], 0.5 op_sel_hi:[1,0,0]
	v_cvt_u32_f32_e32 v160, v28
	v_cvt_u32_f32_e32 v161, v20
	v_cvt_u32_f32_e32 v162, v24
	v_cvt_u32_f32_e32 v163, v16
	v_cvt_u32_f32_sdwa v160, v29 dst_sel:BYTE_1 dst_unused:UNUSED_PRESERVE src0_sel:DWORD
	v_cvt_u32_f32_sdwa v161, v21 dst_sel:BYTE_1 dst_unused:UNUSED_PRESERVE src0_sel:DWORD
	v_cvt_u32_f32_sdwa v162, v25 dst_sel:BYTE_1 dst_unused:UNUSED_PRESERVE src0_sel:DWORD
	v_cvt_u32_f32_sdwa v163, v17 dst_sel:BYTE_1 dst_unused:UNUSED_PRESERVE src0_sel:DWORD
	v_cvt_u32_f32_sdwa v160, v30 dst_sel:BYTE_2 dst_unused:UNUSED_PRESERVE src0_sel:DWORD
	v_cvt_u32_f32_sdwa v161, v22 dst_sel:BYTE_2 dst_unused:UNUSED_PRESERVE src0_sel:DWORD
	v_cvt_u32_f32_sdwa v162, v26 dst_sel:BYTE_2 dst_unused:UNUSED_PRESERVE src0_sel:DWORD
	v_cvt_u32_f32_sdwa v163, v18 dst_sel:BYTE_2 dst_unused:UNUSED_PRESERVE src0_sel:DWORD
	v_cvt_u32_f32_sdwa v160, v31 dst_sel:BYTE_3 dst_unused:UNUSED_PRESERVE src0_sel:DWORD
	v_cvt_u32_f32_sdwa v161, v23 dst_sel:BYTE_3 dst_unused:UNUSED_PRESERVE src0_sel:DWORD
	v_cvt_u32_f32_sdwa v162, v27 dst_sel:BYTE_3 dst_unused:UNUSED_PRESERVE src0_sel:DWORD
	v_cvt_u32_f32_sdwa v163, v19 dst_sel:BYTE_3 dst_unused:UNUSED_PRESERVE src0_sel:DWORD
	s_nop 0
	global_store_dwordx4 v148, v[160:163], s[66:67] nt
	s_add_u32 s66, s66, 0x2c000
	s_addc_u32 s67, s67, 0
	v_pk_mul_f32 v[0:1], v[0:1], s[68:69] op_sel_hi:[1,0]
	v_pk_mul_f32 v[2:3], v[2:3], s[68:69] op_sel_hi:[1,0]
	v_pk_mul_f32 v[4:5], v[4:5], s[68:69] op_sel_hi:[1,0]
	v_pk_mul_f32 v[6:7], v[6:7], s[68:69] op_sel_hi:[1,0]
	v_pk_mul_f32 v[8:9], v[8:9], s[68:69] op_sel_hi:[1,0]
	v_pk_mul_f32 v[10:11], v[10:11], s[68:69] op_sel_hi:[1,0]
	v_pk_mul_f32 v[12:13], v[12:13], s[68:69] op_sel_hi:[1,0]
	v_pk_mul_f32 v[14:15], v[14:15], s[68:69] op_sel_hi:[1,0]
	v_exp_f32_e32 v0, v0
	v_exp_f32_e32 v1, v1
	v_exp_f32_e32 v2, v2
	v_exp_f32_e32 v3, v3
	v_exp_f32_e32 v4, v4
	v_exp_f32_e32 v5, v5
	v_exp_f32_e32 v6, v6
	v_exp_f32_e32 v7, v7
	v_exp_f32_e32 v8, v8
	v_exp_f32_e32 v9, v9
	v_exp_f32_e32 v10, v10
	v_exp_f32_e32 v11, v11
	v_exp_f32_e32 v12, v12
	v_exp_f32_e32 v13, v13
	v_exp_f32_e32 v14, v14
	v_exp_f32_e32 v15, v15
	v_pk_add_f32 v[0:1], v[0:1], 1.0 op_sel_hi:[1,0]
	v_pk_add_f32 v[2:3], v[2:3], 1.0 op_sel_hi:[1,0]
	v_pk_add_f32 v[4:5], v[4:5], 1.0 op_sel_hi:[1,0]
	v_pk_add_f32 v[6:7], v[6:7], 1.0 op_sel_hi:[1,0]
	v_pk_add_f32 v[8:9], v[8:9], 1.0 op_sel_hi:[1,0]
	v_pk_add_f32 v[10:11], v[10:11], 1.0 op_sel_hi:[1,0]
	v_pk_add_f32 v[12:13], v[12:13], 1.0 op_sel_hi:[1,0]
	v_pk_add_f32 v[14:15], v[14:15], 1.0 op_sel_hi:[1,0]
	v_rcp_f32_e32 v0, v0
	v_rcp_f32_e32 v1, v1
	v_rcp_f32_e32 v2, v2
	v_rcp_f32_e32 v3, v3
	v_rcp_f32_e32 v4, v4
	v_rcp_f32_e32 v5, v5
	v_rcp_f32_e32 v6, v6
	v_rcp_f32_e32 v7, v7
	v_rcp_f32_e32 v8, v8
	v_rcp_f32_e32 v9, v9
	v_rcp_f32_e32 v10, v10
	v_rcp_f32_e32 v11, v11
	v_rcp_f32_e32 v12, v12
	v_rcp_f32_e32 v13, v13
	v_rcp_f32_e32 v14, v14
	v_rcp_f32_e32 v15, v15
	v_pk_fma_f32 v[0:1], v[0:1], s[24:25], 0.5 op_sel_hi:[1,0,0]
	v_pk_fma_f32 v[2:3], v[2:3], s[24:25], 0.5 op_sel_hi:[1,0,0]
	v_pk_fma_f32 v[4:5], v[4:5], s[24:25], 0.5 op_sel_hi:[1,0,0]
	v_pk_fma_f32 v[6:7], v[6:7], s[24:25], 0.5 op_sel_hi:[1,0,0]
	v_pk_fma_f32 v[8:9], v[8:9], s[24:25], 0.5 op_sel_hi:[1,0,0]
	v_pk_fma_f32 v[10:11], v[10:11], s[24:25], 0.5 op_sel_hi:[1,0,0]
	v_pk_fma_f32 v[12:13], v[12:13], s[24:25], 0.5 op_sel_hi:[1,0,0]
	v_pk_fma_f32 v[14:15], v[14:15], s[24:25], 0.5 op_sel_hi:[1,0,0]
	v_cvt_u32_f32_e32 v164, v12
	v_cvt_u32_f32_e32 v165, v4
	v_cvt_u32_f32_e32 v166, v8
	v_cvt_u32_f32_e32 v167, v0
	v_cvt_u32_f32_sdwa v164, v13 dst_sel:BYTE_1 dst_unused:UNUSED_PRESERVE src0_sel:DWORD
	v_cvt_u32_f32_sdwa v165, v5 dst_sel:BYTE_1 dst_unused:UNUSED_PRESERVE src0_sel:DWORD
	v_cvt_u32_f32_sdwa v166, v9 dst_sel:BYTE_1 dst_unused:UNUSED_PRESERVE src0_sel:DWORD
	v_cvt_u32_f32_sdwa v167, v1 dst_sel:BYTE_1 dst_unused:UNUSED_PRESERVE src0_sel:DWORD
	v_cvt_u32_f32_sdwa v164, v14 dst_sel:BYTE_2 dst_unused:UNUSED_PRESERVE src0_sel:DWORD
	v_cvt_u32_f32_sdwa v165, v6 dst_sel:BYTE_2 dst_unused:UNUSED_PRESERVE src0_sel:DWORD
	v_cvt_u32_f32_sdwa v166, v10 dst_sel:BYTE_2 dst_unused:UNUSED_PRESERVE src0_sel:DWORD
	v_cvt_u32_f32_sdwa v167, v2 dst_sel:BYTE_2 dst_unused:UNUSED_PRESERVE src0_sel:DWORD
	v_cvt_u32_f32_sdwa v164, v15 dst_sel:BYTE_3 dst_unused:UNUSED_PRESERVE src0_sel:DWORD
	v_cvt_u32_f32_sdwa v165, v7 dst_sel:BYTE_3 dst_unused:UNUSED_PRESERVE src0_sel:DWORD
	v_cvt_u32_f32_sdwa v166, v11 dst_sel:BYTE_3 dst_unused:UNUSED_PRESERVE src0_sel:DWORD
	v_cvt_u32_f32_sdwa v167, v3 dst_sel:BYTE_3 dst_unused:UNUSED_PRESERVE src0_sel:DWORD
	s_nop 0
	global_store_dwordx4 v148, v[164:167], s[66:67] nt
	s_mov_b64 s[2:3], 0
